# D3 store waves issue L2 prefetch loads 2 chunks ahead of the loader (quarter of the shared operand streams per v-slice workgroup); weight-conversion loads/stores marked nt
# speedup vs baseline: 1.0193x; 1.0101x over previous
; DI void wave_lds_fence() { __builtin_amdgcn_fence(__ATOMIC_RELEASE, "wavefront"); __builtin_amdgcn_wave_barrier(); __builtin_amdgcn_fence(__ATOMIC_ACQUIRE, "wavefront"); }
; template <int MODE> DI void transpose_item(const float* __restrict__ W, int K, int N, bf16_t* WT, LAS float* scr, int item, int lane) {
;     const int nblk = (N + 31) / 32, kb = item / nblk, nb = item % nblk, k0 = 64 * kb, n0 = 32 * nb;
;     const int ncol = n0 + (lane & 31); const bool okc = ncol < N;
;     float tv[32];
; #pragma unroll
;     for (int i = 0; i < 32; ++i) { const int kk = 2 * i + (lane >> 5); tv[i] = okc ? W[(size_t)(k0 + kk) * N + ncol] : 0.f; }
; #pragma unroll
;     for (int i = 0; i < 32; ++i) { const int kk = 2 * i + (lane >> 5); scr[kk * 33 + (lane & 31)] = tv[i]; }
;     wave_lds_fence();
; DI void convert_items(const Params& P, LAS unsigned char* lds, int it0, int it1, int gw, int NGW, int wave, int lane) {
;     ...
;     for (int it = it0 + gw; it < it1; it += NGW) {
;         const int l = it / I_L; int r = it % I_L;
;         if (r < I_IN) { transpose_item<1>(P.w_in + (size_t)l * D * INC, D, INC, WIN + (size_t)l * NPROJ * D, scr, r, lane); continue; } r -= I_IN;
;         if (r < I_OUT) { transpose_item<0>(P.w_out + (size_t)l * D * D, D, D, WOUT + (size_t)l * D * D, scr, r, lane); continue; } r -= I_OUT;
;         if (r < I_GU) { transpose_item<2>(P.w_gu + (size_t)l * D * NGU, D, NGU, WGU + (size_t)l * NGU * D, scr, r, lane); continue; } r -= I_GU;
;         transpose_item<0>(P.w_dn + (size_t)l * FF * D, FF, D, WDN + (size_t)l * D * FF, scr, r, lane);
.LBB0_229:
	s_mul_hi_i32 s0, s13, 0x561e46a5
	s_lshr_b32 s1, s0, 31
	s_ashr_i32 s0, s0, 13
	s_add_i32 s4, s0, s1
	s_mul_i32 s0, s4, 0xffffa0e0
	s_add_i32 s8, s13, s0
	s_cmpk_gt_i32 s8, 0x151f
	s_mov_b64 s[0:1], -1
	s_cbranch_scc0 .LBB0_239
	s_cmpk_gt_u32 s8, 0x1d1f
	s_cbranch_scc0 .LBB0_236
	s_cmpk_gt_u32 s8, 0x491f
	s_mul_hi_i32 s9, s4, 0x2c00000
	s_mul_i32 s5, s4, 0x2c00000
	s_cbranch_scc0 .LBB0_233
	v_readlane_b32 s48, v254, 32
	s_add_i32 s10, s8, 0xffffb6e0
	v_readlane_b32 s60, v254, 44
	v_readlane_b32 s61, v254, 45
	s_add_u32 s0, s60, s5
	s_addc_u32 s1, s61, s9
	s_mul_i32 s39, s4, 0x1600000
	s_mul_hi_i32 s11, s4, 0x1600000
	s_add_u32 s39, s34, s39
	s_addc_u32 s11, s36, s11
	s_and_b32 s40, s10, 0x1fc0
	s_lshl_b32 s10, s4, 10
	s_sub_i32 s10, s37, s10
	s_add_i32 s10, s10, 0xfff98000
	s_and_b32 s10, s10, 0x7e0
	v_or_b32_e32 v2, s40, v14
	v_lshl_or_b32 v2, v2, 11, s10
	v_or_b32_e32 v3, v2, v1
	v_or_b32_e32 v4, v2, v15
	v_or_b32_e32 v5, v2, v16
	v_or_b32_e32 v6, v2, v17
	v_or_b32_e32 v7, v2, v18
	v_or_b32_e32 v8, v2, v19
	v_or_b32_e32 v9, v2, v20
	v_or_b32_e32 v10, v2, v21
	v_lshlrev_b32_e32 v3, 2, v3
	v_lshlrev_b32_e32 v4, 2, v4
	v_lshlrev_b32_e32 v5, 2, v5
	v_lshlrev_b32_e32 v6, 2, v6
	v_lshlrev_b32_e32 v7, 2, v7
	v_lshlrev_b32_e32 v8, 2, v8
	v_lshlrev_b32_e32 v9, 2, v9
	v_lshlrev_b32_e32 v10, 2, v10
	global_load_dword v3, v3, s[0:1] nt
	s_nop 0
	global_load_dword v4, v4, s[0:1] nt
	s_nop 0
	global_load_dword v5, v5, s[0:1] nt
	s_nop 0
	global_load_dword v6, v6, s[0:1] nt
	s_nop 0
	global_load_dword v7, v7, s[0:1] nt
	s_nop 0
	global_load_dword v8, v8, s[0:1] nt
	s_nop 0
	global_load_dword v9, v9, s[0:1] nt
	s_nop 0
	global_load_dword v10, v10, s[0:1] nt
	v_or_b32_e32 v11, v2, v22
	v_or_b32_e32 v12, v2, v23
	v_or_b32_e32 v13, v2, v24
	v_or_b32_e32 v52, v2, v25
	v_or_b32_e32 v53, v2, v26
	v_or_b32_e32 v54, v2, v27
	v_or_b32_e32 v55, v2, v28
	v_or_b32_e32 v56, v2, v29
	v_lshlrev_b32_e32 v11, 2, v11
	v_lshlrev_b32_e32 v12, 2, v12
	v_lshlrev_b32_e32 v13, 2, v13
	v_lshlrev_b32_e32 v52, 2, v52
	v_lshlrev_b32_e32 v53, 2, v53
	v_lshlrev_b32_e32 v54, 2, v54
	v_lshlrev_b32_e32 v55, 2, v55
	v_lshlrev_b32_e32 v56, 2, v56
	global_load_dword v11, v11, s[0:1] nt
	s_nop 0
	global_load_dword v12, v12, s[0:1] nt
	s_nop 0
	global_load_dword v13, v13, s[0:1] nt
	s_nop 0
	global_load_dword v52, v52, s[0:1] nt
	s_nop 0
	global_load_dword v53, v53, s[0:1] nt
	s_nop 0
	global_load_dword v54, v54, s[0:1] nt
	s_nop 0
	global_load_dword v55, v55, s[0:1] nt
	s_nop 0
	global_load_dword v56, v56, s[0:1] nt
	v_or_b32_e32 v57, v2, v30
	v_or_b32_e32 v58, v2, v31
	v_or_b32_e32 v59, v2, v32
	v_or_b32_e32 v60, v2, v33
	v_or_b32_e32 v61, v2, v34
	v_or_b32_e32 v62, v2, v35
	v_or_b32_e32 v63, v2, v36
	v_or_b32_e32 v64, v2, v37
	v_lshlrev_b32_e32 v57, 2, v57
	v_lshlrev_b32_e32 v58, 2, v58
	v_lshlrev_b32_e32 v59, 2, v59
	v_lshlrev_b32_e32 v60, 2, v60
	v_lshlrev_b32_e32 v61, 2, v61
	v_lshlrev_b32_e32 v62, 2, v62
	v_lshlrev_b32_e32 v63, 2, v63
	v_lshlrev_b32_e32 v64, 2, v64
	global_load_dword v57, v57, s[0:1] nt
	s_nop 0
	global_load_dword v58, v58, s[0:1] nt
	s_nop 0
	global_load_dword v59, v59, s[0:1] nt
	s_nop 0
	global_load_dword v60, v60, s[0:1] nt
	s_nop 0
	global_load_dword v61, v61, s[0:1] nt
	s_nop 0
	global_load_dword v62, v62, s[0:1] nt
	s_nop 0
	global_load_dword v63, v63, s[0:1] nt
	s_nop 0
	global_load_dword v64, v64, s[0:1] nt
	v_or_b32_e32 v65, v2, v38
	v_or_b32_e32 v66, v2, v39
	v_or_b32_e32 v67, v2, v40
	v_or_b32_e32 v68, v2, v41
	v_or_b32_e32 v69, v2, v42
	v_or_b32_e32 v70, v2, v43
	v_or_b32_e32 v71, v2, v44
	v_or_b32_e32 v2, v2, v45
	v_lshlrev_b32_e32 v65, 2, v65
	v_lshlrev_b32_e32 v66, 2, v66
	v_lshlrev_b32_e32 v67, 2, v67
	v_lshlrev_b32_e32 v68, 2, v68
	v_lshlrev_b32_e32 v69, 2, v69
	v_lshlrev_b32_e32 v70, 2, v70
	v_lshlrev_b32_e32 v71, 2, v71
	v_lshlrev_b32_e32 v2, 2, v2
	global_load_dword v65, v65, s[0:1] nt
	s_nop 0
	global_load_dword v66, v66, s[0:1] nt
	s_nop 0
	global_load_dword v67, v67, s[0:1] nt
	s_nop 0
	global_load_dword v68, v68, s[0:1] nt
	s_nop 0
	global_load_dword v69, v69, s[0:1] nt
	s_nop 0
	global_load_dword v70, v70, s[0:1] nt
	s_nop 0
	global_load_dword v71, v71, s[0:1] nt
	s_nop 0
	global_load_dword v2, v2, s[0:1] nt
	s_lshl_b32 s0, s40, 1
	s_add_u32 s0, s39, s0
	s_addc_u32 s1, s11, 0
	s_waitcnt vmcnt(0)
	ds_write2_b32 v46, v3, v4 offset1:66
	ds_write2_b32 v46, v5, v6 offset0:132 offset1:198
	v_add_u32_e32 v3, 0x400, v46
	ds_write2_b32 v3, v7, v8 offset0:8 offset1:74
	ds_write2_b32 v3, v9, v10 offset0:140 offset1:206
	v_add_u32_e32 v3, 0x800, v46
	ds_write2_b32 v3, v11, v12 offset0:16 offset1:82
	ds_write2_b32 v3, v13, v52 offset0:148 offset1:214
	v_add_u32_e32 v3, 0xc00, v46
	ds_write2_b32 v3, v53, v54 offset0:24 offset1:90
	ds_write2_b32 v3, v55, v56 offset0:156 offset1:222
	v_add_u32_e32 v3, 0x1000, v46
	ds_write2_b32 v3, v57, v58 offset0:32 offset1:98
	ds_write2_b32 v3, v59, v60 offset0:164 offset1:230
	v_add_u32_e32 v3, 0x1400, v46
	ds_write2_b32 v3, v61, v62 offset0:40 offset1:106
	ds_write2_b32 v3, v63, v64 offset0:172 offset1:238
	v_add_u32_e32 v3, 0x1800, v46
	ds_write2_b32 v3, v65, v66 offset0:48 offset1:114
	ds_write2_b32 v3, v67, v68 offset0:180 offset1:246
	v_add_u32_e32 v3, 0x1c00, v46
	ds_write2_b32 v3, v69, v70 offset0:56 offset1:122
	ds_write2_b32 v3, v71, v2 offset0:188 offset1:254
	ds_read2_b32 v[6:7], v48 offset0:33 offset1:41
	ds_read2_b32 v[8:9], v48 offset1:8
	ds_read2_b32 v[10:11], v48 offset0:66 offset1:74
	ds_read2_b32 v[12:13], v48 offset0:99 offset1:107
	ds_read2_b32 v[52:53], v48 offset0:132 offset1:140
	ds_read2_b32 v[54:55], v48 offset0:165 offset1:173
	ds_read2_b32 v[56:57], v48 offset0:198 offset1:206
	ds_read2_b32 v[58:59], v48 offset0:231 offset1:239
	s_waitcnt lgkmcnt(6)
; #define LAS __attribute__((address_space(3)))
; DI unsigned cvtpk(float lo, float hi) { f32x2 v = {lo, hi}; bf16x2_t b = __builtin_convertvector(v, bf16x2_t); return __builtin_bit_cast(unsigned, b); }
; DI void wave_lds_fence() { __builtin_amdgcn_fence(__ATOMIC_RELEASE, "wavefront"); __builtin_amdgcn_wave_barrier(); __builtin_amdgcn_fence(__ATOMIC_ACQUIRE, "wavefront"); }
; template <int MODE> DI void transpose_item(const float* __restrict__ W, int K, int N, bf16_t* WT, LAS float* scr, int item, int lane) {
;     const int nblk = (N + 31) / 32, kb = item / nblk, nb = item % nblk, k0 = 64 * kb, n0 = 32 * nb;
;     const int ncol = n0 + (lane & 31); const bool okc = ncol < N;
;     float tv[32];
; #pragma unroll
;     for (int i = 0; i < 32; ++i) { const int kk = 2 * i + (lane >> 5); tv[i] = okc ? W[(size_t)(k0 + kk) * N + ncol] : 0.f; }
; #pragma unroll
;     for (int i = 0; i < 32; ++i) { const int kk = 2 * i + (lane >> 5); scr[kk * 33 + (lane & 31)] = tv[i]; }
;     wave_lds_fence();
;     const int c = lane & 7;
; #pragma unroll
;     for (int j = 0; j < 4; ++j) { const int n = (lane >> 3) + 8 * j; const LAS float* s = scr + (8 * c) * 33 + n;
;         u32x4 o; o.x = cvtpk(s[0 * 33], s[1 * 33]); o.y = cvtpk(s[2 * 33], s[3 * 33]); o.z = cvtpk(s[4 * 33], s[5 * 33]); o.w = cvtpk(s[6 * 33], s[7 * 33]);
;         const int nsrc = n0 + n;
;         if (nsrc < N) { const int nd = MODE == 1 ? map_in(nsrc) : (MODE == 2 ? map_gu(nsrc) : nsrc); *(u32x4*)(WT + (size_t)nd * K + k0 + 8 * c) = o; } }
	v_cvt_pk_bf16_f32 v2, v8, v6
	v_or_b32_e32 v6, s10, v47
	v_lshlrev_b32_e32 v96, 1, v0
	v_mul_u32_u24_e32 v6, 0x1600, v6
	v_lshl_add_u64 v[60:61], s[0:1], 0, v[96:97]
	v_lshlrev_b32_e32 v96, 1, v6
	s_waitcnt lgkmcnt(4)
	v_cvt_pk_bf16_f32 v3, v10, v12
	s_waitcnt lgkmcnt(2)
	v_cvt_pk_bf16_f32 v4, v52, v54
	s_waitcnt lgkmcnt(0)
	v_cvt_pk_bf16_f32 v5, v56, v58
	v_lshl_add_u64 v[62:63], v[60:61], 0, v[96:97]
	v_or_b32_e32 v6, s10, v49
	global_store_dwordx4 v[62:63], v[2:5], off nt
	v_mul_u32_u24_e32 v6, 0x1600, v6
	v_lshlrev_b32_e32 v96, 1, v6
	v_cvt_pk_bf16_f32 v2, v9, v7
	v_cvt_pk_bf16_f32 v3, v11, v13
	v_cvt_pk_bf16_f32 v4, v53, v55
	v_cvt_pk_bf16_f32 v5, v57, v59
	ds_read2_b32 v[8:9], v48 offset0:16 offset1:24
	ds_read2_b32 v[10:11], v48 offset0:49 offset1:57
	ds_read2_b32 v[12:13], v48 offset0:82 offset1:90
	ds_read2_b32 v[52:53], v48 offset0:115 offset1:123
	ds_read2_b32 v[54:55], v48 offset0:148 offset1:156
	ds_read2_b32 v[56:57], v48 offset0:181 offset1:189
	ds_read2_b32 v[58:59], v48 offset0:214 offset1:222
	ds_read2_b32 v[62:63], v48 offset0:247 offset1:255
	v_lshl_add_u64 v[6:7], v[60:61], 0, v[96:97]
	global_store_dwordx4 v[6:7], v[2:5], off nt
	v_or_b32_e32 v6, s10, v50
	v_mul_u32_u24_e32 v6, 0x1600, v6
	v_lshlrev_b32_e32 v96, 1, v6
	s_waitcnt lgkmcnt(6)
	v_cvt_pk_bf16_f32 v2, v8, v10
	s_waitcnt lgkmcnt(4)
	v_cvt_pk_bf16_f32 v3, v12, v52
	s_waitcnt lgkmcnt(2)
	v_cvt_pk_bf16_f32 v4, v54, v56
	s_waitcnt lgkmcnt(0)
	v_cvt_pk_bf16_f32 v5, v58, v62
	v_lshl_add_u64 v[6:7], v[60:61], 0, v[96:97]
	global_store_dwordx4 v[6:7], v[2:5], off nt
	v_or_b32_e32 v6, s10, v51
	v_mul_u32_u24_e32 v6, 0x1600, v6
	v_lshlrev_b32_e32 v96, 1, v6
	v_cvt_pk_bf16_f32 v2, v9, v11
	v_cvt_pk_bf16_f32 v3, v13, v53
	v_cvt_pk_bf16_f32 v4, v55, v57
	v_cvt_pk_bf16_f32 v5, v59, v63
	v_lshl_add_u64 v[6:7], v[60:61], 0, v[96:97]
	v_readlane_b32 s49, v254, 33
	v_readlane_b32 s50, v254, 34
	v_readlane_b32 s51, v254, 35
	v_readlane_b32 s52, v254, 36
	v_readlane_b32 s53, v254, 37
	v_readlane_b32 s54, v254, 38
	v_readlane_b32 s55, v254, 39
	v_readlane_b32 s56, v254, 40
	v_readlane_b32 s57, v254, 41
	v_readlane_b32 s58, v254, 42
	v_readlane_b32 s59, v254, 43
	v_readlane_b32 s62, v254, 46
	v_readlane_b32 s63, v254, 47
	global_store_dwordx4 v[6:7], v[2:5], off nt
	s_mov_b64 s[0:1], 0
.LBB0_233:
	s_andn2_b64 vcc, exec, s[0:1]
	s_cbranch_vccnz .LBB0_235
	v_readlane_b32 s48, v254, 32
	s_mul_i32 s1, s4, 0x5800000
	v_readlane_b32 s58, v254, 42
	s_mul_hi_i32 s0, s4, 0x5800000
	v_readlane_b32 s59, v254, 43
	s_add_u32 s40, s58, s1
	s_addc_u32 s41, s59, s0
	s_add_u32 s5, s22, s5
	s_addc_u32 s9, s23, s9
	s_add_i32 s0, s8, 0xe2e0
	s_and_b32 s1, s0, 0xffff
	s_mul_i32 s1, s1, 0xba2f
	s_lshr_b32 s10, s1, 24
	s_mul_i32 s1, s10, 0x160
	s_sub_i32 s1, s0, s1
	s_lshl_b32 s0, s1, 5
	s_and_b32 s0, s0, 0xffe0
	v_lshl_or_b32 v3, s10, 6, v14
	v_or_b32_e32 v2, s0, v1
	v_mul_u32_u24_e32 v3, 0x2c00, v3
	v_add_lshl_u32 v96, v2, v3, 2
	v_lshl_add_u64 v[2:3], s[40:41], 0, v[96:97]
	s_mov_b32 s11, 0x16000
	v_add_co_u32_e32 v4, vcc, s11, v2
	s_mov_b32 s11, 0x2c000
	s_nop 0
	v_addc_co_u32_e32 v5, vcc, 0, v3, vcc
	global_load_dword v7, v[4:5], off nt
	v_add_co_u32_e32 v4, vcc, s11, v2
	s_mov_b32 s11, 0x42000
	s_nop 0
	v_addc_co_u32_e32 v5, vcc, 0, v3, vcc
	global_load_dword v8, v[4:5], off nt
	v_add_co_u32_e32 v4, vcc, s11, v2
	s_mov_b32 s11, 0x58000
	s_nop 0
	v_addc_co_u32_e32 v5, vcc, 0, v3, vcc
	global_load_dword v9, v[4:5], off nt
	v_add_co_u32_e32 v4, vcc, s11, v2
	s_mov_b32 s11, 0x6e000
	s_nop 0
	v_addc_co_u32_e32 v5, vcc, 0, v3, vcc
	global_load_dword v10, v[4:5], off nt
	v_add_co_u32_e32 v4, vcc, s11, v2
	s_mov_b32 s11, 0x84000
	s_nop 0
	v_addc_co_u32_e32 v5, vcc, 0, v3, vcc
	global_load_dword v11, v[4:5], off nt
	v_add_co_u32_e32 v4, vcc, s11, v2
	s_mov_b32 s11, 0x9a000
	s_nop 0
	v_addc_co_u32_e32 v5, vcc, 0, v3, vcc
	global_load_dword v12, v[4:5], off nt
	v_add_co_u32_e32 v4, vcc, s11, v2
	s_mov_b32 s11, 0xb0000
	s_nop 0
	v_addc_co_u32_e32 v5, vcc, 0, v3, vcc
	global_load_dword v13, v[4:5], off nt
	v_add_co_u32_e32 v4, vcc, s11, v2
	s_mov_b32 s11, 0xc6000
	s_nop 0
	v_addc_co_u32_e32 v5, vcc, 0, v3, vcc
	global_load_dword v52, v[4:5], off nt
	v_add_co_u32_e32 v4, vcc, s11, v2
	s_mov_b32 s11, 0xdc000
	s_nop 0
	v_addc_co_u32_e32 v5, vcc, 0, v3, vcc
	global_load_dword v53, v[4:5], off nt
	v_add_co_u32_e32 v4, vcc, s11, v2
	s_mov_b32 s11, 0xf2000
	s_nop 0
	v_addc_co_u32_e32 v5, vcc, 0, v3, vcc
	global_load_dword v54, v[4:5], off nt
	v_add_co_u32_e32 v4, vcc, s11, v2
	s_mov_b32 s11, 0x108000
	s_nop 0
	v_addc_co_u32_e32 v5, vcc, 0, v3, vcc
	global_load_dword v55, v[4:5], off nt
	v_add_co_u32_e32 v4, vcc, s11, v2
	s_mov_b32 s11, 0x11e000
	s_nop 0
	v_addc_co_u32_e32 v5, vcc, 0, v3, vcc
	global_load_dword v56, v[4:5], off nt
	v_add_co_u32_e32 v4, vcc, s11, v2
	s_mov_b32 s11, 0x134000
	s_nop 0
	v_addc_co_u32_e32 v5, vcc, 0, v3, vcc
	global_load_dword v57, v[4:5], off nt
	v_add_co_u32_e32 v4, vcc, s11, v2
	s_mov_b32 s11, 0x14a000
	s_nop 0
	v_addc_co_u32_e32 v5, vcc, 0, v3, vcc
	global_load_dword v58, v[4:5], off nt
	v_add_co_u32_e32 v4, vcc, s11, v2
	s_mov_b32 s11, 0x160000
	s_nop 0
	v_addc_co_u32_e32 v5, vcc, 0, v3, vcc
	global_load_dword v59, v[4:5], off nt
	v_add_co_u32_e32 v4, vcc, s11, v2
	s_mov_b32 s11, 0x176000
	s_nop 0
	v_addc_co_u32_e32 v5, vcc, 0, v3, vcc
	global_load_dword v60, v[4:5], off nt
	v_add_co_u32_e32 v4, vcc, s11, v2
	s_mov_b32 s11, 0x18c000
	s_nop 0
	v_addc_co_u32_e32 v5, vcc, 0, v3, vcc
	global_load_dword v61, v[4:5], off nt
	v_add_co_u32_e32 v4, vcc, s11, v2
	s_mov_b32 s11, 0x1a2000
	s_nop 0
	v_addc_co_u32_e32 v5, vcc, 0, v3, vcc
	global_load_dword v62, v[4:5], off nt
; #define LAS __attribute__((address_space(3)))
; DI unsigned cvtpk(float lo, float hi) { f32x2 v = {lo, hi}; bf16x2_t b = __builtin_convertvector(v, bf16x2_t); return __builtin_bit_cast(unsigned, b); }
; DI void wave_lds_fence() { __builtin_amdgcn_fence(__ATOMIC_RELEASE, "wavefront"); __builtin_amdgcn_wave_barrier(); __builtin_amdgcn_fence(__ATOMIC_ACQUIRE, "wavefront"); }
; template <int MODE> DI void transpose_item(const float* __restrict__ W, int K, int N, bf16_t* WT, LAS float* scr, int item, int lane) {
;     const int nblk = (N + 31) / 32, kb = item / nblk, nb = item % nblk, k0 = 64 * kb, n0 = 32 * nb;
;     const int ncol = n0 + (lane & 31); const bool okc = ncol < N;
;     float tv[32];
; #pragma unroll
;     for (int i = 0; i < 32; ++i) { const int kk = 2 * i + (lane >> 5); tv[i] = okc ? W[(size_t)(k0 + kk) * N + ncol] : 0.f; }
; #pragma unroll
;     for (int i = 0; i < 32; ++i) { const int kk = 2 * i + (lane >> 5); scr[kk * 33 + (lane & 31)] = tv[i]; }
;     wave_lds_fence();
;     const int c = lane & 7;
; #pragma unroll
;     for (int j = 0; j < 4; ++j) { const int n = (lane >> 3) + 8 * j; const LAS float* s = scr + (8 * c) * 33 + n;
;         u32x4 o; o.x = cvtpk(s[0 * 33], s[1 * 33]); o.y = cvtpk(s[2 * 33], s[3 * 33]); o.z = cvtpk(s[4 * 33], s[5 * 33]); o.w = cvtpk(s[6 * 33], s[7 * 33]);
;         const int nsrc = n0 + n;
;         if (nsrc < N) { const int nd = MODE == 1 ? map_in(nsrc) : (MODE == 2 ? map_gu(nsrc) : nsrc); *(u32x4*)(WT + (size_t)nd * K + k0 + 8 * c) = o; } }
	v_add_co_u32_e32 v4, vcc, s11, v2
	s_mov_b32 s11, 0x1b8000
	s_nop 0
	v_addc_co_u32_e32 v5, vcc, 0, v3, vcc
	global_load_dword v63, v[4:5], off nt
	v_add_co_u32_e32 v4, vcc, s11, v2
	s_mov_b32 s11, 0x1ce000
	s_nop 0
	v_addc_co_u32_e32 v5, vcc, 0, v3, vcc
	global_load_dword v64, v[4:5], off nt
	v_add_co_u32_e32 v4, vcc, s11, v2
	s_mov_b32 s11, 0x1e4000
	s_nop 0
	v_addc_co_u32_e32 v5, vcc, 0, v3, vcc
	global_load_dword v65, v[4:5], off nt
	v_add_co_u32_e32 v4, vcc, s11, v2
	s_mov_b32 s11, 0x1fa000
	s_nop 0
	v_addc_co_u32_e32 v5, vcc, 0, v3, vcc
	global_load_dword v66, v[4:5], off nt
	v_add_co_u32_e32 v4, vcc, s11, v2
	s_mov_b32 s11, 0x210000
	s_nop 0
	v_addc_co_u32_e32 v5, vcc, 0, v3, vcc
	global_load_dword v67, v[4:5], off nt
	v_add_co_u32_e32 v4, vcc, s11, v2
	s_mov_b32 s11, 0x226000
	s_nop 0
	v_addc_co_u32_e32 v5, vcc, 0, v3, vcc
	global_load_dword v68, v[4:5], off nt
	v_add_co_u32_e32 v4, vcc, s11, v2
	s_mov_b32 s11, 0x23c000
	s_nop 0
	v_addc_co_u32_e32 v5, vcc, 0, v3, vcc
	global_load_dword v69, v[4:5], off nt
	v_add_co_u32_e32 v4, vcc, s11, v2
	s_mov_b32 s11, 0x252000
	s_nop 0
	v_addc_co_u32_e32 v5, vcc, 0, v3, vcc
	global_load_dword v70, v[4:5], off nt
	v_add_co_u32_e32 v4, vcc, s11, v2
	s_mov_b32 s11, 0x268000
	s_nop 0
	v_addc_co_u32_e32 v5, vcc, 0, v3, vcc
	global_load_dword v71, v[4:5], off nt
	v_add_co_u32_e32 v4, vcc, s11, v2
	global_load_dword v6, v96, s[40:41] nt
	s_nop 0
	v_addc_co_u32_e32 v5, vcc, 0, v3, vcc
	s_mov_b32 s11, 0x27e000
	global_load_dword v72, v[4:5], off nt
	v_add_co_u32_e32 v4, vcc, s11, v2
	s_mov_b32 s11, 0x294000
	s_nop 0
	v_addc_co_u32_e32 v5, vcc, 0, v3, vcc
	global_load_dword v73, v[4:5], off nt
	v_add_co_u32_e32 v4, vcc, s11, v2
	s_mov_b32 s11, 0x2aa000
	s_nop 0
	v_addc_co_u32_e32 v5, vcc, 0, v3, vcc
	v_add_co_u32_e32 v2, vcc, s11, v2
	global_load_dword v4, v[4:5], off nt
	s_nop 0
	v_addc_co_u32_e32 v3, vcc, 0, v3, vcc
	global_load_dword v2, v[2:3], off nt
	v_add_u32_e32 v3, 0x400, v46
	s_waitcnt vmcnt(0)
	ds_write2_b32 v46, v6, v7 offset1:66
	ds_write2_b32 v46, v8, v9 offset0:132 offset1:198
	ds_write2_b32 v3, v10, v11 offset0:8 offset1:74
	ds_write2_b32 v3, v12, v13 offset0:140 offset1:206
	v_add_u32_e32 v3, 0x800, v46
	ds_write2_b32 v3, v52, v53 offset0:16 offset1:82
	ds_write2_b32 v3, v54, v55 offset0:148 offset1:214
	v_add_u32_e32 v3, 0xc00, v46
	ds_write2_b32 v3, v56, v57 offset0:24 offset1:90
	ds_write2_b32 v3, v58, v59 offset0:156 offset1:222
	v_add_u32_e32 v3, 0x1000, v46
	ds_write2_b32 v3, v60, v61 offset0:32 offset1:98
	ds_write2_b32 v3, v62, v63 offset0:164 offset1:230
	v_add_u32_e32 v3, 0x1400, v46
	ds_write2_b32 v3, v64, v65 offset0:40 offset1:106
	ds_write2_b32 v3, v66, v67 offset0:172 offset1:238
	v_add_u32_e32 v3, 0x1800, v46
	ds_write2_b32 v3, v68, v69 offset0:48 offset1:114
	ds_write2_b32 v3, v70, v71 offset0:180 offset1:246
	v_add_u32_e32 v3, 0x1c00, v46
	ds_write2_b32 v3, v72, v73 offset0:56 offset1:122
	ds_write2_b32 v3, v4, v2 offset0:188 offset1:254
	ds_read2_b32 v[8:9], v48 offset0:33 offset1:41
	ds_read2_b32 v[10:11], v48 offset1:8
	s_lshl_b32 s10, s10, 7
	s_add_u32 s10, s5, s10
	s_addc_u32 s11, s9, 0
	s_and_b32 s1, s1, 0xffff
	s_waitcnt lgkmcnt(0)
	v_cvt_pk_bf16_f32 v2, v10, v8
	v_or_b32_e32 v8, s0, v47
	s_cmpk_gt_u32 s1, 0xaf
	s_cselect_b64 vcc, -1, 0
	v_add_u32_e32 v10, 0xffffea00, v8
	v_lshlrev_b32_e32 v96, 1, v0
	v_cndmask_b32_e32 v8, v8, v10, vcc
	v_lshl_add_u64 v[6:7], s[10:11], 0, v[96:97]
	ds_read2_b32 v[12:13], v48 offset0:66 offset1:74
	ds_read2_b32 v[52:53], v48 offset0:99 offset1:107
	ds_read2_b32 v[54:55], v48 offset0:132 offset1:140
	ds_read2_b32 v[56:57], v48 offset0:165 offset1:173
	ds_read2_b32 v[58:59], v48 offset0:198 offset1:206
	ds_read2_b32 v[60:61], v48 offset0:231 offset1:239
	v_lshlrev_b32_e32 v10, 1, v8
	s_and_b64 s[10:11], vcc, exec
	v_and_b32_e32 v10, 0xffffff00, v10
	s_cselect_b32 s1, 0x80, 0
	v_and_b32_e32 v8, 0x67, v8
	v_or3_b32 v62, v8, v10, s1
	v_ashrrev_i32_e32 v63, 31, v62
	v_lshlrev_b64 v[62:63], 12, v[62:63]
	s_waitcnt lgkmcnt(4)
	v_cvt_pk_bf16_f32 v3, v12, v52
	s_waitcnt lgkmcnt(2)
	v_cvt_pk_bf16_f32 v4, v54, v56
	s_waitcnt lgkmcnt(0)
	v_cvt_pk_bf16_f32 v5, v58, v60
	v_lshl_add_u64 v[62:63], v[6:7], 0, v[62:63]
	v_or_b32_e32 v8, s0, v49
	global_store_dwordx4 v[62:63], v[2:5], off nt
	v_readlane_b32 s49, v254, 33
	v_readlane_b32 s50, v254, 34
	v_cvt_pk_bf16_f32 v2, v11, v9
	v_add_u32_e32 v9, 0xffffea00, v8
	v_cndmask_b32_e32 v8, v8, v9, vcc
	v_lshlrev_b32_e32 v9, 1, v8
	v_and_b32_e32 v9, 0xffffff00, v9
	v_and_b32_e32 v8, 0x6f, v8
	v_or3_b32 v8, v8, v9, s1
	v_ashrrev_i32_e32 v9, 31, v8
	v_lshlrev_b64 v[8:9], 12, v[8:9]
	v_cvt_pk_bf16_f32 v3, v13, v53
	v_cvt_pk_bf16_f32 v4, v55, v57
	v_cvt_pk_bf16_f32 v5, v59, v61
	v_lshl_add_u64 v[8:9], v[6:7], 0, v[8:9]
	global_store_dwordx4 v[8:9], v[2:5], off nt
	ds_read2_b32 v[8:9], v48 offset0:16 offset1:24
	ds_read2_b32 v[10:11], v48 offset0:49 offset1:57
	ds_read2_b32 v[12:13], v48 offset0:82 offset1:90
	ds_read2_b32 v[52:53], v48 offset0:115 offset1:123
	ds_read2_b32 v[54:55], v48 offset0:148 offset1:156
	ds_read2_b32 v[56:57], v48 offset0:181 offset1:189
	ds_read2_b32 v[58:59], v48 offset0:214 offset1:222
	ds_read2_b32 v[60:61], v48 offset0:247 offset1:255
	v_readlane_b32 s51, v254, 35
	s_waitcnt lgkmcnt(6)
	v_cvt_pk_bf16_f32 v2, v8, v10
	v_or_b32_e32 v8, s0, v50
	v_add_u32_e32 v10, 0xffffea00, v8
	v_cndmask_b32_e32 v8, v8, v10, vcc
	v_lshlrev_b32_e32 v10, 1, v8
	v_and_b32_e32 v10, 0xffffff00, v10
	v_and_b32_e32 v8, 0x77, v8
	v_or3_b32 v62, v8, v10, s1
	v_ashrrev_i32_e32 v63, 31, v62
	v_lshlrev_b64 v[62:63], 12, v[62:63]
	s_waitcnt lgkmcnt(4)
	v_cvt_pk_bf16_f32 v3, v12, v52
	s_waitcnt lgkmcnt(2)
	v_cvt_pk_bf16_f32 v4, v54, v56
	s_waitcnt lgkmcnt(0)
	v_cvt_pk_bf16_f32 v5, v58, v60
	v_lshl_add_u64 v[62:63], v[6:7], 0, v[62:63]
	v_or_b32_e32 v8, s0, v51
	global_store_dwordx4 v[62:63], v[2:5], off nt
	v_readlane_b32 s52, v254, 36
	v_readlane_b32 s53, v254, 37
	v_cvt_pk_bf16_f32 v2, v9, v11
	v_add_u32_e32 v9, 0xffffea00, v8
	v_cndmask_b32_e32 v8, v8, v9, vcc
	v_lshlrev_b32_e32 v9, 1, v8
	v_and_b32_e32 v9, 0xffffff00, v9
	v_and_b32_e32 v8, 0x7f, v8
	v_or3_b32 v8, v8, v9, s1
	v_ashrrev_i32_e32 v9, 31, v8
	v_lshlrev_b64 v[8:9], 12, v[8:9]
	v_cvt_pk_bf16_f32 v3, v13, v53
	v_cvt_pk_bf16_f32 v4, v55, v57
	v_cvt_pk_bf16_f32 v5, v59, v61
	v_lshl_add_u64 v[6:7], v[6:7], 0, v[8:9]
	v_readlane_b32 s54, v254, 38
	v_readlane_b32 s55, v254, 39
	v_readlane_b32 s56, v254, 40
	v_readlane_b32 s57, v254, 41
	v_readlane_b32 s60, v254, 44
	v_readlane_b32 s61, v254, 45
	v_readlane_b32 s62, v254, 46
	v_readlane_b32 s63, v254, 47
	global_store_dwordx4 v[6:7], v[2:5], off nt

; template <int MODE> DI void transpose_item(const float* __restrict__ W, int K, int N, bf16_t* WT, LAS float* scr, int item, int lane) {
;     const int nblk = (N + 31) / 32, kb = item / nblk, nb = item % nblk, k0 = 64 * kb, n0 = 32 * nb;
;     const int ncol = n0 + (lane & 31); const bool okc = ncol < N;
;     float tv[32];
; #pragma unroll
;     for (int i = 0; i < 32; ++i) { const int kk = 2 * i + (lane >> 5); tv[i] = okc ? W[(size_t)(k0 + kk) * N + ncol] : 0.f; }
; #pragma unroll
;     for (int i = 0; i < 32; ++i) { const int kk = 2 * i + (lane >> 5); scr[kk * 33 + (lane & 31)] = tv[i]; }
.LBB0_236:
	s_andn2_b64 vcc, exec, s[0:1]
	s_cbranch_vccnz .LBB0_238
	s_ashr_i32 s5, s4, 31
	v_readlane_b32 s48, v254, 32
	s_add_i32 s9, s8, 0xffffeae0
	s_lshl_b64 s[0:1], s[4:5], 24
	v_readlane_b32 s56, v254, 40
	v_readlane_b32 s57, v254, 41
	s_add_u32 s0, s56, s0
	s_addc_u32 s1, s57, s1
	s_lshl_b64 s[10:11], s[4:5], 23
	s_add_u32 s10, s19, s10
	s_addc_u32 s11, s20, s11
	s_lshl_b32 s5, s4, 10
	s_and_b32 s9, s9, 0x1fc0
	s_sub_i32 s5, s37, s5
	s_and_b32 s5, s5, 0x7e0
	v_or_b32_e32 v2, s9, v14
	v_lshl_or_b32 v2, v2, 11, s5
	v_or_b32_e32 v3, v2, v1
	v_or_b32_e32 v4, v2, v15
	v_or_b32_e32 v5, v2, v16
	v_or_b32_e32 v6, v2, v17
	v_or_b32_e32 v7, v2, v18
	v_or_b32_e32 v8, v2, v19
	v_or_b32_e32 v9, v2, v20
	v_or_b32_e32 v10, v2, v21
	v_lshlrev_b32_e32 v3, 2, v3
	v_lshlrev_b32_e32 v4, 2, v4
	v_lshlrev_b32_e32 v5, 2, v5
	v_lshlrev_b32_e32 v6, 2, v6
	v_lshlrev_b32_e32 v7, 2, v7
	v_lshlrev_b32_e32 v8, 2, v8
	v_lshlrev_b32_e32 v9, 2, v9
	v_lshlrev_b32_e32 v10, 2, v10
	global_load_dword v3, v3, s[0:1] nt
	s_nop 0
	global_load_dword v4, v4, s[0:1] nt
	s_nop 0
	global_load_dword v5, v5, s[0:1] nt
	s_nop 0
	global_load_dword v6, v6, s[0:1] nt
	s_nop 0
	global_load_dword v7, v7, s[0:1] nt
	s_nop 0
	global_load_dword v8, v8, s[0:1] nt
	s_nop 0
	global_load_dword v9, v9, s[0:1] nt
	s_nop 0
	global_load_dword v10, v10, s[0:1] nt
	v_or_b32_e32 v11, v2, v22
	v_or_b32_e32 v12, v2, v23
	v_or_b32_e32 v13, v2, v24
	v_or_b32_e32 v52, v2, v25
	v_or_b32_e32 v53, v2, v26
	v_or_b32_e32 v54, v2, v27
	v_or_b32_e32 v55, v2, v28
	v_or_b32_e32 v56, v2, v29
	v_lshlrev_b32_e32 v11, 2, v11
	v_lshlrev_b32_e32 v12, 2, v12
	v_lshlrev_b32_e32 v13, 2, v13
	v_lshlrev_b32_e32 v52, 2, v52
	v_lshlrev_b32_e32 v53, 2, v53
	v_lshlrev_b32_e32 v54, 2, v54
	v_lshlrev_b32_e32 v55, 2, v55
	v_lshlrev_b32_e32 v56, 2, v56
	global_load_dword v11, v11, s[0:1] nt
	s_nop 0
	global_load_dword v12, v12, s[0:1] nt
	s_nop 0
	global_load_dword v13, v13, s[0:1] nt
	s_nop 0
	global_load_dword v52, v52, s[0:1] nt
	s_nop 0
	global_load_dword v53, v53, s[0:1] nt
	s_nop 0
	global_load_dword v54, v54, s[0:1] nt
	s_nop 0
	global_load_dword v55, v55, s[0:1] nt
	s_nop 0
	global_load_dword v56, v56, s[0:1] nt
	v_or_b32_e32 v57, v2, v30
	v_or_b32_e32 v58, v2, v31
	v_or_b32_e32 v59, v2, v32
	v_or_b32_e32 v60, v2, v33
	v_or_b32_e32 v61, v2, v34
	v_or_b32_e32 v62, v2, v35
	v_or_b32_e32 v63, v2, v36
	v_or_b32_e32 v64, v2, v37
	v_lshlrev_b32_e32 v57, 2, v57
	v_lshlrev_b32_e32 v58, 2, v58
	v_lshlrev_b32_e32 v59, 2, v59
	v_lshlrev_b32_e32 v60, 2, v60
	v_lshlrev_b32_e32 v61, 2, v61
	v_lshlrev_b32_e32 v62, 2, v62
	v_lshlrev_b32_e32 v63, 2, v63
	v_lshlrev_b32_e32 v64, 2, v64
	global_load_dword v57, v57, s[0:1] nt
	s_nop 0
	global_load_dword v58, v58, s[0:1] nt
	s_nop 0
	global_load_dword v59, v59, s[0:1] nt
	s_nop 0
	global_load_dword v60, v60, s[0:1] nt
	s_nop 0
	global_load_dword v61, v61, s[0:1] nt
	s_nop 0
	global_load_dword v62, v62, s[0:1] nt
	s_nop 0
	global_load_dword v63, v63, s[0:1] nt
	s_nop 0
	global_load_dword v64, v64, s[0:1] nt
	v_or_b32_e32 v65, v2, v38
	v_or_b32_e32 v66, v2, v39
	v_or_b32_e32 v67, v2, v40
	v_or_b32_e32 v68, v2, v41
	v_or_b32_e32 v69, v2, v42
	v_or_b32_e32 v70, v2, v43
	v_or_b32_e32 v71, v2, v44
	v_or_b32_e32 v2, v2, v45
	v_lshlrev_b32_e32 v65, 2, v65
	v_lshlrev_b32_e32 v66, 2, v66
	v_lshlrev_b32_e32 v67, 2, v67
	v_lshlrev_b32_e32 v68, 2, v68
	v_lshlrev_b32_e32 v69, 2, v69
	v_lshlrev_b32_e32 v70, 2, v70
	v_lshlrev_b32_e32 v71, 2, v71
	v_lshlrev_b32_e32 v2, 2, v2
	global_load_dword v65, v65, s[0:1] nt
	s_nop 0
	global_load_dword v66, v66, s[0:1] nt
	s_nop 0
	global_load_dword v67, v67, s[0:1] nt
	s_nop 0
	global_load_dword v68, v68, s[0:1] nt
	s_nop 0
	global_load_dword v69, v69, s[0:1] nt
	s_nop 0
	global_load_dword v70, v70, s[0:1] nt
	s_nop 0
	global_load_dword v71, v71, s[0:1] nt
	s_nop 0
	global_load_dword v2, v2, s[0:1] nt
	s_lshl_b32 s0, s9, 1
	s_add_u32 s0, s10, s0
	s_waitcnt vmcnt(0)
; #define LAS __attribute__((address_space(3)))
; DI unsigned cvtpk(float lo, float hi) { f32x2 v = {lo, hi}; bf16x2_t b = __builtin_convertvector(v, bf16x2_t); return __builtin_bit_cast(unsigned, b); }
; DI void wave_lds_fence() { __builtin_amdgcn_fence(__ATOMIC_RELEASE, "wavefront"); __builtin_amdgcn_wave_barrier(); __builtin_amdgcn_fence(__ATOMIC_ACQUIRE, "wavefront"); }
; template <int MODE> DI void transpose_item(const float* __restrict__ W, int K, int N, bf16_t* WT, LAS float* scr, int item, int lane) {
;     ...
;     for (int i = 0; i < 32; ++i) { const int kk = 2 * i + (lane >> 5); scr[kk * 33 + (lane & 31)] = tv[i]; }
;     wave_lds_fence();
;     const int c = lane & 7;
; #pragma unroll
;     for (int j = 0; j < 4; ++j) { const int n = (lane >> 3) + 8 * j; const LAS float* s = scr + (8 * c) * 33 + n;
;         u32x4 o; o.x = cvtpk(s[0 * 33], s[1 * 33]); o.y = cvtpk(s[2 * 33], s[3 * 33]); o.z = cvtpk(s[4 * 33], s[5 * 33]); o.w = cvtpk(s[6 * 33], s[7 * 33]);
;         const int nsrc = n0 + n;
;         if (nsrc < N) { const int nd = MODE == 1 ? map_in(nsrc) : (MODE == 2 ? map_gu(nsrc) : nsrc); *(u32x4*)(WT + (size_t)nd * K + k0 + 8 * c) = o; } }
	ds_write2_b32 v46, v3, v4 offset1:66
	ds_write2_b32 v46, v5, v6 offset0:132 offset1:198
	v_add_u32_e32 v3, 0x400, v46
	ds_write2_b32 v3, v7, v8 offset0:8 offset1:74
	ds_write2_b32 v3, v9, v10 offset0:140 offset1:206
	v_add_u32_e32 v3, 0x800, v46
	ds_write2_b32 v3, v11, v12 offset0:16 offset1:82
	ds_write2_b32 v3, v13, v52 offset0:148 offset1:214
	v_add_u32_e32 v3, 0xc00, v46
	ds_write2_b32 v3, v53, v54 offset0:24 offset1:90
	ds_write2_b32 v3, v55, v56 offset0:156 offset1:222
	v_add_u32_e32 v3, 0x1000, v46
	ds_write2_b32 v3, v57, v58 offset0:32 offset1:98
	ds_write2_b32 v3, v59, v60 offset0:164 offset1:230
	v_add_u32_e32 v3, 0x1400, v46
	ds_write2_b32 v3, v61, v62 offset0:40 offset1:106
	ds_write2_b32 v3, v63, v64 offset0:172 offset1:238
	v_add_u32_e32 v3, 0x1800, v46
	ds_write2_b32 v3, v65, v66 offset0:48 offset1:114
	ds_write2_b32 v3, v67, v68 offset0:180 offset1:246
	v_add_u32_e32 v3, 0x1c00, v46
	ds_write2_b32 v3, v69, v70 offset0:56 offset1:122
	ds_write2_b32 v3, v71, v2 offset0:188 offset1:254
	ds_read2_b32 v[6:7], v48 offset0:33 offset1:41
	ds_read2_b32 v[8:9], v48 offset1:8
	ds_read2_b32 v[10:11], v48 offset0:66 offset1:74
	ds_read2_b32 v[12:13], v48 offset0:99 offset1:107
	ds_read2_b32 v[52:53], v48 offset0:132 offset1:140
	ds_read2_b32 v[54:55], v48 offset0:165 offset1:173
	ds_read2_b32 v[56:57], v48 offset0:198 offset1:206
	ds_read2_b32 v[58:59], v48 offset0:231 offset1:239
	s_addc_u32 s1, s11, 0
	v_lshlrev_b32_e32 v96, 1, v0
	s_waitcnt lgkmcnt(6)
	v_cvt_pk_bf16_f32 v2, v8, v6
	v_or_b32_e32 v6, s5, v47
	v_lshl_add_u64 v[60:61], s[0:1], 0, v[96:97]
	v_lshlrev_b32_e32 v96, 12, v6
	s_waitcnt lgkmcnt(4)
	v_cvt_pk_bf16_f32 v3, v10, v12
	s_waitcnt lgkmcnt(2)
	v_cvt_pk_bf16_f32 v4, v52, v54
	s_waitcnt lgkmcnt(0)
	v_cvt_pk_bf16_f32 v5, v56, v58
	v_lshl_add_u64 v[62:63], v[60:61], 0, v[96:97]
	global_store_dwordx4 v[62:63], v[2:5], off nt
	v_or_b32_e32 v6, s5, v49
	v_lshlrev_b32_e32 v96, 12, v6
	v_cvt_pk_bf16_f32 v2, v9, v7
	v_cvt_pk_bf16_f32 v3, v11, v13
	v_cvt_pk_bf16_f32 v4, v53, v55
	v_cvt_pk_bf16_f32 v5, v57, v59
	ds_read2_b32 v[8:9], v48 offset0:49 offset1:57
	ds_read2_b32 v[10:11], v48 offset0:16 offset1:24
	ds_read2_b32 v[12:13], v48 offset0:82 offset1:90
	ds_read2_b32 v[52:53], v48 offset0:115 offset1:123
	ds_read2_b32 v[54:55], v48 offset0:148 offset1:156
	ds_read2_b32 v[56:57], v48 offset0:181 offset1:189
	ds_read2_b32 v[58:59], v48 offset0:214 offset1:222
	ds_read2_b32 v[62:63], v48 offset0:247 offset1:255
	v_lshl_add_u64 v[6:7], v[60:61], 0, v[96:97]
	global_store_dwordx4 v[6:7], v[2:5], off nt
	v_or_b32_e32 v6, s5, v50
	v_lshlrev_b32_e32 v96, 12, v6
	s_waitcnt lgkmcnt(6)
	v_cvt_pk_bf16_f32 v2, v10, v8
	s_waitcnt lgkmcnt(4)
	v_cvt_pk_bf16_f32 v3, v12, v52
	s_waitcnt lgkmcnt(2)
	v_cvt_pk_bf16_f32 v4, v54, v56
	s_waitcnt lgkmcnt(0)
	v_cvt_pk_bf16_f32 v5, v58, v62
	v_lshl_add_u64 v[6:7], v[60:61], 0, v[96:97]
	global_store_dwordx4 v[6:7], v[2:5], off nt
	v_or_b32_e32 v6, s5, v51
	v_lshlrev_b32_e32 v96, 12, v6
	v_cvt_pk_bf16_f32 v2, v11, v9
	v_cvt_pk_bf16_f32 v3, v13, v53
	v_cvt_pk_bf16_f32 v4, v55, v57
	v_cvt_pk_bf16_f32 v5, v59, v63
	v_lshl_add_u64 v[6:7], v[60:61], 0, v[96:97]
	v_readlane_b32 s49, v254, 33
	v_readlane_b32 s50, v254, 34
	v_readlane_b32 s51, v254, 35
	v_readlane_b32 s52, v254, 36
	v_readlane_b32 s53, v254, 37
	v_readlane_b32 s54, v254, 38
	v_readlane_b32 s55, v254, 39
	v_readlane_b32 s58, v254, 42
	v_readlane_b32 s59, v254, 43
	v_readlane_b32 s60, v254, 44
	v_readlane_b32 s61, v254, 45
	v_readlane_b32 s62, v254, 46
	v_readlane_b32 s63, v254, 47
	global_store_dwordx4 v[6:7], v[2:5], off nt

; template <int MODE> DI void transpose_item(const float* __restrict__ W, int K, int N, bf16_t* WT, LAS float* scr, int item, int lane) {
;     const int nblk = (N + 31) / 32, kb = item / nblk, nb = item % nblk, k0 = 64 * kb, n0 = 32 * nb;
;     const int ncol = n0 + (lane & 31); const bool okc = ncol < N;
;     float tv[32];
; #pragma unroll
;     for (int i = 0; i < 32; ++i) { const int kk = 2 * i + (lane >> 5); tv[i] = okc ? W[(size_t)(k0 + kk) * N + ncol] : 0.f; }
.LBB0_239:
	s_andn2_b64 vcc, exec, s[0:1]
	s_cbranch_vccnz .LBB0_228
	v_readlane_b32 s48, v253, 55
	s_mul_i32 s1, s4, 0x2a20000
	v_readlane_b32 s60, v254, 3
	s_mul_hi_i32 s0, s4, 0x2a20000
	v_readlane_b32 s61, v254, 4
	s_add_u32 s10, s60, s1
	s_addc_u32 s11, s61, s0
	s_mul_i32 s0, s8, 0x60f3
	s_lshr_b32 s1, s0, 31
	s_ashr_i32 s0, s0, 22
	s_add_i32 s0, s0, s1
	s_mul_i32 s1, s0, 0xa9
	s_sub_i32 s1, s8, s1
	s_sext_i32_i16 s1, s1
	s_lshl_b32 s8, s0, 6
	s_lshl_b32 s39, s1, 5
	v_or_b32_e32 v2, s39, v1
	v_or_b32_e32 v4, s8, v14
	v_ashrrev_i32_e32 v3, 31, v2
	v_mul_i32_i24_e32 v4, 0x5440, v4
	v_cmp_gt_i32_e64 s[0:1], s33, v2
	v_lshl_add_u64 v[2:3], v[2:3], 2, s[10:11]
	v_mov_b32_e32 v7, 0
	v_ashrrev_i32_e32 v5, 31, v4
	v_mov_b32_e32 v6, 0
	v_readlane_b32 s49, v253, 56
	v_readlane_b32 s50, v253, 57
	v_readlane_b32 s51, v253, 58
	v_readlane_b32 s52, v253, 59
	v_readlane_b32 s53, v253, 60
	v_readlane_b32 s54, v253, 61
	v_readlane_b32 s55, v253, 62
	v_readlane_b32 s56, v253, 63
	v_readlane_b32 s57, v254, 0
	v_readlane_b32 s58, v254, 1
	v_readlane_b32 s59, v254, 2
	v_readlane_b32 s62, v254, 5
	v_readlane_b32 s63, v254, 6
	s_and_saveexec_b64 s[10:11], s[0:1]
	s_cbranch_execz .LBB0_242
	v_lshl_add_u64 v[8:9], v[2:3], 0, v[4:5]
	global_load_dword v6, v[8:9], off nt
.LBB0_242:
	s_or_b64 exec, exec, s[10:11]
	s_and_saveexec_b64 s[10:11], s[0:1]
	s_cbranch_execz .LBB0_244
	v_lshl_add_u64 v[8:9], v[2:3], 0, v[4:5]
	v_add_co_u32_e32 v8, vcc, 0xa000, v8
	s_nop 1
	v_addc_co_u32_e32 v9, vcc, 0, v9, vcc
	global_load_dword v7, v[8:9], off offset:2176 nt
.LBB0_244:
	s_or_b64 exec, exec, s[10:11]
	v_mov_b32_e32 v8, 0
	v_mov_b32_e32 v9, 0
	s_and_saveexec_b64 s[10:11], s[0:1]
	s_cbranch_execz .LBB0_246
	v_lshl_add_u64 v[10:11], v[2:3], 0, v[4:5]
	v_add_co_u32_e32 v10, vcc, 0x15000, v10
	s_nop 1
	v_addc_co_u32_e32 v11, vcc, 0, v11, vcc
	global_load_dword v9, v[10:11], off offset:256 nt
.LBB0_246:
	s_or_b64 exec, exec, s[10:11]
	s_and_saveexec_b64 s[10:11], s[0:1]
	s_cbranch_execz .LBB0_248
	v_lshl_add_u64 v[10:11], v[2:3], 0, v[4:5]
	v_add_co_u32_e32 v10, vcc, 0x1f000, v10
	s_nop 1
	v_addc_co_u32_e32 v11, vcc, 0, v11, vcc
	global_load_dword v8, v[10:11], off offset:2432 nt
.LBB0_248:
	s_or_b64 exec, exec, s[10:11]
	v_mov_b32_e32 v10, 0
	v_mov_b32_e32 v11, 0
	s_and_saveexec_b64 s[10:11], s[0:1]
	s_cbranch_execz .LBB0_250
	v_lshl_add_u64 v[12:13], v[2:3], 0, v[4:5]
	v_add_co_u32_e32 v12, vcc, 0x2a000, v12
	s_nop 1
	v_addc_co_u32_e32 v13, vcc, 0, v13, vcc
	global_load_dword v11, v[12:13], off offset:512 nt
.LBB0_250:
	s_or_b64 exec, exec, s[10:11]
	s_and_saveexec_b64 s[10:11], s[0:1]
	s_cbranch_execz .LBB0_252
	v_lshl_add_u64 v[12:13], v[2:3], 0, v[4:5]
	v_add_co_u32_e32 v12, vcc, 0x34000, v12
	s_nop 1
	v_addc_co_u32_e32 v13, vcc, 0, v13, vcc
	global_load_dword v10, v[12:13], off offset:2688 nt
.LBB0_252:
	s_or_b64 exec, exec, s[10:11]
	v_mov_b32_e32 v12, 0
	v_mov_b32_e32 v13, 0
	s_and_saveexec_b64 s[10:11], s[0:1]
	s_cbranch_execz .LBB0_254
	v_lshl_add_u64 v[52:53], v[2:3], 0, v[4:5]
	v_add_co_u32_e32 v52, vcc, 0x3f000, v52
	s_nop 1
	v_addc_co_u32_e32 v53, vcc, 0, v53, vcc
	global_load_dword v13, v[52:53], off offset:768 nt
.LBB0_254:
	s_or_b64 exec, exec, s[10:11]
	s_and_saveexec_b64 s[10:11], s[0:1]
	s_cbranch_execz .LBB0_256
	v_lshl_add_u64 v[52:53], v[2:3], 0, v[4:5]
	v_add_co_u32_e32 v52, vcc, 0x49000, v52
	s_nop 1
	v_addc_co_u32_e32 v53, vcc, 0, v53, vcc
	global_load_dword v12, v[52:53], off offset:2944 nt
.LBB0_256:
	s_or_b64 exec, exec, s[10:11]
	v_mov_b32_e32 v52, 0
	v_mov_b32_e32 v53, 0
	s_and_saveexec_b64 s[10:11], s[0:1]
	s_cbranch_execz .LBB0_258
	v_lshl_add_u64 v[54:55], v[2:3], 0, v[4:5]
	v_add_co_u32_e32 v54, vcc, 0x54000, v54
	s_nop 1
	v_addc_co_u32_e32 v55, vcc, 0, v55, vcc
	global_load_dword v53, v[54:55], off offset:1024 nt
.LBB0_258:
	s_or_b64 exec, exec, s[10:11]
	s_and_saveexec_b64 s[10:11], s[0:1]
	s_cbranch_execz .LBB0_260
	v_lshl_add_u64 v[54:55], v[2:3], 0, v[4:5]
	v_add_co_u32_e32 v54, vcc, 0x5e000, v54
	s_nop 1
	v_addc_co_u32_e32 v55, vcc, 0, v55, vcc
	global_load_dword v52, v[54:55], off offset:3200 nt
.LBB0_260:
	s_or_b64 exec, exec, s[10:11]
	v_mov_b32_e32 v54, 0
	v_mov_b32_e32 v55, 0
	s_and_saveexec_b64 s[10:11], s[0:1]
	s_cbranch_execz .LBB0_262
	v_lshl_add_u64 v[56:57], v[2:3], 0, v[4:5]
	v_add_co_u32_e32 v56, vcc, 0x69000, v56
	s_nop 1
	v_addc_co_u32_e32 v57, vcc, 0, v57, vcc
	global_load_dword v55, v[56:57], off offset:1280 nt
.LBB0_262:
	s_or_b64 exec, exec, s[10:11]
	s_and_saveexec_b64 s[10:11], s[0:1]
	s_cbranch_execz .LBB0_264
	v_lshl_add_u64 v[56:57], v[2:3], 0, v[4:5]
	v_add_co_u32_e32 v56, vcc, 0x73000, v56
	s_nop 1
	v_addc_co_u32_e32 v57, vcc, 0, v57, vcc
	global_load_dword v54, v[56:57], off offset:3456 nt
.LBB0_264:
	s_or_b64 exec, exec, s[10:11]
	v_mov_b32_e32 v56, 0
	v_mov_b32_e32 v57, 0
	s_and_saveexec_b64 s[10:11], s[0:1]
	s_cbranch_execz .LBB0_266
	v_lshl_add_u64 v[58:59], v[2:3], 0, v[4:5]
	v_add_co_u32_e32 v58, vcc, 0x7e000, v58
	s_nop 1
	v_addc_co_u32_e32 v59, vcc, 0, v59, vcc
	global_load_dword v57, v[58:59], off offset:1536 nt
.LBB0_266:
	s_or_b64 exec, exec, s[10:11]
	s_and_saveexec_b64 s[10:11], s[0:1]
	s_cbranch_execz .LBB0_268
	v_lshl_add_u64 v[58:59], v[2:3], 0, v[4:5]
	v_add_co_u32_e32 v58, vcc, 0x88000, v58
	s_nop 1
	v_addc_co_u32_e32 v59, vcc, 0, v59, vcc
	global_load_dword v56, v[58:59], off offset:3712 nt
.LBB0_268:
	s_or_b64 exec, exec, s[10:11]
	v_mov_b32_e32 v58, 0
	v_mov_b32_e32 v59, 0
	s_and_saveexec_b64 s[10:11], s[0:1]
	s_cbranch_execz .LBB0_270
	v_lshl_add_u64 v[60:61], v[2:3], 0, v[4:5]
	v_add_co_u32_e32 v60, vcc, 0x93000, v60
	s_nop 1
	v_addc_co_u32_e32 v61, vcc, 0, v61, vcc
	global_load_dword v59, v[60:61], off offset:1792 nt
; template <int MODE> DI void transpose_item(const float* __restrict__ W, int K, int N, bf16_t* WT, LAS float* scr, int item, int lane) {
;     ...
;     float tv[32];
; #pragma unroll
;     for (int i = 0; i < 32; ++i) { const int kk = 2 * i + (lane >> 5); tv[i] = okc ? W[(size_t)(k0 + kk) * N + ncol] : 0.f; }
.LBB0_270:
	s_or_b64 exec, exec, s[10:11]
	s_and_saveexec_b64 s[10:11], s[0:1]
	s_cbranch_execz .LBB0_272
	v_lshl_add_u64 v[60:61], v[2:3], 0, v[4:5]
	v_add_co_u32_e32 v60, vcc, 0x9d000, v60
	s_nop 1
	v_addc_co_u32_e32 v61, vcc, 0, v61, vcc
	global_load_dword v58, v[60:61], off offset:3968 nt
.LBB0_272:
	s_or_b64 exec, exec, s[10:11]
	v_mov_b32_e32 v60, 0
	v_mov_b32_e32 v61, 0
	s_and_saveexec_b64 s[10:11], s[0:1]
	s_cbranch_execz .LBB0_274
	v_lshl_add_u64 v[62:63], v[2:3], 0, v[4:5]
	v_add_co_u32_e32 v62, vcc, 0xa8000, v62
	s_nop 1
	v_addc_co_u32_e32 v63, vcc, 0, v63, vcc
	global_load_dword v61, v[62:63], off offset:2048 nt
.LBB0_274:
	s_or_b64 exec, exec, s[10:11]
	s_and_saveexec_b64 s[10:11], s[0:1]
	s_cbranch_execz .LBB0_276
	v_lshl_add_u64 v[62:63], v[2:3], 0, v[4:5]
	v_add_co_u32_e32 v62, vcc, 0xb3000, v62
	s_nop 1
	v_addc_co_u32_e32 v63, vcc, 0, v63, vcc
	global_load_dword v60, v[62:63], off offset:128 nt
.LBB0_276:
	s_or_b64 exec, exec, s[10:11]
	v_mov_b32_e32 v62, 0
	v_mov_b32_e32 v63, 0
	s_and_saveexec_b64 s[10:11], s[0:1]
	s_cbranch_execz .LBB0_278
	v_lshl_add_u64 v[64:65], v[2:3], 0, v[4:5]
	v_add_co_u32_e32 v64, vcc, 0xbd000, v64
	s_nop 1
	v_addc_co_u32_e32 v65, vcc, 0, v65, vcc
	global_load_dword v63, v[64:65], off offset:2304 nt
.LBB0_278:
	s_or_b64 exec, exec, s[10:11]
	s_and_saveexec_b64 s[10:11], s[0:1]
	s_cbranch_execz .LBB0_280
	v_lshl_add_u64 v[64:65], v[2:3], 0, v[4:5]
	v_add_co_u32_e32 v64, vcc, 0xc8000, v64
	s_nop 1
	v_addc_co_u32_e32 v65, vcc, 0, v65, vcc
	global_load_dword v62, v[64:65], off offset:384 nt
.LBB0_280:
	s_or_b64 exec, exec, s[10:11]
	v_mov_b32_e32 v64, 0
	v_mov_b32_e32 v65, 0
	s_and_saveexec_b64 s[10:11], s[0:1]
	s_cbranch_execz .LBB0_282
	v_lshl_add_u64 v[66:67], v[2:3], 0, v[4:5]
	v_add_co_u32_e32 v66, vcc, 0xd2000, v66
	s_nop 1
	v_addc_co_u32_e32 v67, vcc, 0, v67, vcc
	global_load_dword v65, v[66:67], off offset:2560 nt
.LBB0_282:
	s_or_b64 exec, exec, s[10:11]
	s_and_saveexec_b64 s[10:11], s[0:1]
	s_cbranch_execz .LBB0_284
	v_lshl_add_u64 v[66:67], v[2:3], 0, v[4:5]
	v_add_co_u32_e32 v66, vcc, 0xdd000, v66
	s_nop 1
	v_addc_co_u32_e32 v67, vcc, 0, v67, vcc
	global_load_dword v64, v[66:67], off offset:640 nt
.LBB0_284:
	s_or_b64 exec, exec, s[10:11]
	v_mov_b32_e32 v66, 0
	v_mov_b32_e32 v67, 0
	s_and_saveexec_b64 s[10:11], s[0:1]
	s_cbranch_execz .LBB0_286
	v_lshl_add_u64 v[68:69], v[2:3], 0, v[4:5]
	v_add_co_u32_e32 v68, vcc, 0xe7000, v68
	s_nop 1
	v_addc_co_u32_e32 v69, vcc, 0, v69, vcc
	global_load_dword v67, v[68:69], off offset:2816 nt
.LBB0_286:
	s_or_b64 exec, exec, s[10:11]
	s_and_saveexec_b64 s[10:11], s[0:1]
	s_cbranch_execz .LBB0_288
	v_lshl_add_u64 v[68:69], v[2:3], 0, v[4:5]
	v_add_co_u32_e32 v68, vcc, 0xf2000, v68
	s_nop 1
	v_addc_co_u32_e32 v69, vcc, 0, v69, vcc
	global_load_dword v66, v[68:69], off offset:896 nt
.LBB0_288:
	s_or_b64 exec, exec, s[10:11]
	v_mov_b32_e32 v68, 0
	v_mov_b32_e32 v69, 0
	s_and_saveexec_b64 s[10:11], s[0:1]
	s_cbranch_execz .LBB0_290
	v_lshl_add_u64 v[70:71], v[2:3], 0, v[4:5]
	v_add_co_u32_e32 v70, vcc, 0xfc000, v70
	s_nop 1
	v_addc_co_u32_e32 v71, vcc, 0, v71, vcc
	global_load_dword v69, v[70:71], off offset:3072 nt
.LBB0_290:
	s_or_b64 exec, exec, s[10:11]
	s_and_saveexec_b64 s[10:11], s[0:1]
	s_cbranch_execz .LBB0_292
	v_lshl_add_u64 v[70:71], v[2:3], 0, v[4:5]
	v_add_co_u32_e32 v70, vcc, 0x107000, v70
	s_nop 1
	v_addc_co_u32_e32 v71, vcc, 0, v71, vcc
	global_load_dword v68, v[70:71], off offset:1152 nt
.LBB0_292:
	s_or_b64 exec, exec, s[10:11]
	v_mov_b32_e32 v70, 0
	v_mov_b32_e32 v71, 0
	s_and_saveexec_b64 s[10:11], s[0:1]
	s_cbranch_execz .LBB0_294
	v_lshl_add_u64 v[72:73], v[2:3], 0, v[4:5]
	v_add_co_u32_e32 v72, vcc, 0x111000, v72
	s_nop 1
	v_addc_co_u32_e32 v73, vcc, 0, v73, vcc
	global_load_dword v71, v[72:73], off offset:3328 nt
.LBB0_294:
	s_or_b64 exec, exec, s[10:11]
	s_and_saveexec_b64 s[10:11], s[0:1]
	s_cbranch_execz .LBB0_296
	v_lshl_add_u64 v[72:73], v[2:3], 0, v[4:5]
	v_add_co_u32_e32 v72, vcc, 0x11c000, v72
	s_nop 1
	v_addc_co_u32_e32 v73, vcc, 0, v73, vcc
	global_load_dword v70, v[72:73], off offset:1408 nt
.LBB0_296:
	s_or_b64 exec, exec, s[10:11]
	v_mov_b32_e32 v72, 0
	v_mov_b32_e32 v73, 0
	s_and_saveexec_b64 s[10:11], s[0:1]
	s_cbranch_execz .LBB0_298
	v_lshl_add_u64 v[74:75], v[2:3], 0, v[4:5]
	v_add_co_u32_e32 v74, vcc, 0x126000, v74
	s_nop 1
	v_addc_co_u32_e32 v75, vcc, 0, v75, vcc
	global_load_dword v73, v[74:75], off offset:3584 nt
.LBB0_298:
	s_or_b64 exec, exec, s[10:11]
	s_and_saveexec_b64 s[10:11], s[0:1]
	s_cbranch_execz .LBB0_300
	v_lshl_add_u64 v[74:75], v[2:3], 0, v[4:5]
	v_add_co_u32_e32 v74, vcc, 0x131000, v74
	s_nop 1
	v_addc_co_u32_e32 v75, vcc, 0, v75, vcc
	global_load_dword v72, v[74:75], off offset:1664 nt
.LBB0_300:
	s_or_b64 exec, exec, s[10:11]
	v_mov_b32_e32 v74, 0
	v_mov_b32_e32 v75, 0
	s_and_saveexec_b64 s[10:11], s[0:1]
	s_cbranch_execz .LBB0_302
	v_lshl_add_u64 v[76:77], v[2:3], 0, v[4:5]
	v_add_co_u32_e32 v76, vcc, 0x13b000, v76
	s_nop 1
	v_addc_co_u32_e32 v77, vcc, 0, v77, vcc
	global_load_dword v75, v[76:77], off offset:3840 nt
.LBB0_302:
	s_or_b64 exec, exec, s[10:11]
	s_and_saveexec_b64 s[10:11], s[0:1]
	s_cbranch_execz .LBB0_304
	v_lshl_add_u64 v[2:3], v[2:3], 0, v[4:5]
	v_add_co_u32_e32 v2, vcc, 0x146000, v2
	s_nop 1
	v_addc_co_u32_e32 v3, vcc, 0, v3, vcc
	global_load_dword v74, v[2:3], off offset:1920 nt

; DI unsigned cvtpk(float lo, float hi) { f32x2 v = {lo, hi}; bf16x2_t b = __builtin_convertvector(v, bf16x2_t); return __builtin_bit_cast(unsigned, b); }
; template <int MODE> DI void transpose_item(const float* __restrict__ W, int K, int N, bf16_t* WT, LAS float* scr, int item, int lane) {
;     ...
;         u32x4 o; o.x = cvtpk(s[0 * 33], s[1 * 33]); o.y = cvtpk(s[2 * 33], s[3 * 33]); o.z = cvtpk(s[4 * 33], s[5 * 33]); o.w = cvtpk(s[6 * 33], s[7 * 33]);
;         const int nsrc = n0 + n;
;         if (nsrc < N) { const int nd = MODE == 1 ? map_in(nsrc) : (MODE == 2 ? map_gu(nsrc) : nsrc); *(u32x4*)(WT + (size_t)nd * K + k0 + 8 * c) = o; } }
.LBB0_311:
	s_or_b64 exec, exec, s[4:5]
	v_ashrrev_i32_e32 v5, 31, v4
	v_lshlrev_b64 v[4:5], 12, v[4:5]
	s_waitcnt lgkmcnt(3)
	v_cvt_pk_bf16_f32 v13, v12, v13
	s_waitcnt lgkmcnt(2)
	v_cvt_pk_bf16_f32 v12, v10, v11
	s_waitcnt lgkmcnt(1)
	v_cvt_pk_bf16_f32 v11, v8, v9
	s_waitcnt lgkmcnt(0)
	v_cvt_pk_bf16_f32 v10, v6, v7
	v_lshl_add_u64 v[4:5], v[2:3], 0, v[4:5]
	global_store_dwordx4 v[4:5], v[10:13], off nt

; #define D3_BAR() do { asm volatile("s_waitcnt lgkmcnt(0)" ::: "memory"); __builtin_amdgcn_s_barrier(); asm volatile("" ::: "memory"); } while (0)
; DI void d3_block(const Params& P, int bh, int vs, LAS unsigned char* lds, int wave, int lane, int tid) {
;     ...
;         const int row0 = 32 * (wave - 2) + (lane >> 3), col4 = 4 * (lane & 7);
;         float* orow = ODN + (size_t)(b * T + row0) * 1024 + h * 128 + vs * 32 + col4;
;         D3_BAR();
.LBB0_358:
	s_lshl_b32 s0, s6, 5
	s_sub_i32 s0, s0, 64
	v_lshrrev_b32_e32 v0, 3, v240
	v_or_b32_e32 v2, s0, v0
	v_readlane_b32 s0, v253, 2
	v_readlane_b32 s8, v254, 28
	v_readlane_b32 s9, v254, 29
	v_add_u32_e32 v0, s0, v2
	v_ashrrev_i32_e32 v1, 31, v0
	v_readlane_b32 s0, v254, 58
	v_lshlrev_b64 v[0:1], 12, v[0:1]
	v_readlane_b32 s1, v254, 59
	v_readlane_b32 s10, v254, 30
	v_readlane_b32 s11, v254, 31
	v_lshl_add_u64 v[0:1], s[0:1], 0, v[0:1]
	v_readlane_b32 s0, v254, 22
	v_readlane_b32 s1, v254, 23
	s_mov_b32 s4, s0
	v_writelane_b32 v254, s0, 22
	s_mov_b32 s5, s9
	v_lshl_add_u64 v[0:1], v[0:1], 0, s[4:5]
	v_writelane_b32 v254, s1, 23
	s_waitcnt lgkmcnt(0)
	s_barrier
	v_readlane_b32 s0, v254, 24
	v_readlane_b32 s1, v254, 25
	s_mov_b32 s4, s0
	v_writelane_b32 v254, s0, 24
	v_lshl_add_u64 v[0:1], v[0:1], 0, s[4:5]
	v_and_b32_e32 v96, 0x70, v64
	v_writelane_b32 v254, s1, 25
	s_movk_i32 s0, 0x90
	v_mul_lo_u32 v2, v2, s0
	v_readlane_b32 s0, v254, 20
	v_lshl_add_u64 v[0:1], v[0:1], 0, v[96:97]
	s_movk_i32 s8, 0xffc0
	v_add3_u32 v2, s0, v96, v2
	s_mov_b32 s4, -1
	v_readlane_b32 s36, v254, 56
	v_readlane_b32 s37, v254, 57
	v_readlane_b32 s38, v254, 10
	v_readlane_b32 s39, v254, 11
	s_add_u32 s36, s36, s38
	s_addc_u32 s37, s37, s39
	v_readlane_b32 s38, v254, 8
	s_add_u32 s36, s36, s38
	s_addc_u32 s37, s37, 0
	s_add_u32 s36, s36, 0x10000
	s_addc_u32 s37, s37, 0
	v_readlane_b32 s40, v254, 56
	v_readlane_b32 s41, v254, 57
	v_readlane_b32 s42, v253, 21
	v_readlane_b32 s43, v253, 22
	s_add_u32 s40, s40, s42
	s_addc_u32 s41, s41, s43
	s_lshr_b32 s38, s38, 1
	s_add_u32 s40, s40, s38
	s_addc_u32 s41, s41, 0
	s_add_u32 s40, s40, 0x29108000
	s_addc_u32 s41, s41, 0
	v_lshlrev_b32_e32 v220, 4, v240
	s_lshl_b32 s38, s6, 10
	s_add_i32 s38, s38, 0xfffff800
	s_nop 0
	v_add_u32_e32 v220, s38, v220
	s_mov_b32 s44, 2
.Ld3_pf_warm:
	s_add_u32 s38, s36, 0x21100000
	s_addc_u32 s39, s37, 0
	s_add_u32 s42, s36, 0x23100000
	s_addc_u32 s43, s37, 0
	global_load_dwordx4 v[216:219], v220, s[38:39]
	global_load_dwordx4 v[216:219], v220, s[38:39] offset:2048
	global_load_dwordx4 v[216:219], v220, s[42:43]
	global_load_dwordx4 v[216:219], v220, s[42:43] offset:2048
	s_add_u32 s38, s36, 0x25100000
	s_addc_u32 s39, s37, 0
	s_add_u32 s42, s36, 0x27100000
	s_addc_u32 s43, s37, 0
	global_load_dwordx4 v[216:219], v220, s[38:39]
	global_load_dwordx4 v[216:219], v220, s[38:39] offset:2048
	global_load_dwordx4 v[216:219], v220, s[42:43]
	global_load_dwordx4 v[216:219], v220, s[42:43] offset:2048
	global_load_dwordx4 v[216:219], v220, s[40:41]
	s_add_u32 s36, s36, 0x4000
	s_addc_u32 s37, s37, 0
	s_add_u32 s40, s40, 0x2000
	s_addc_u32 s41, s41, 0
	s_add_i32 s44, s44, -1
	s_cmp_lg_u32 s44, 0
	s_cbranch_scc1 .Ld3_pf_warm
	s_branch .LBB0_361

; #define LAS __attribute__((address_space(3)))
; #define D3_BAR() do { asm volatile("s_waitcnt lgkmcnt(0)" ::: "memory"); __builtin_amdgcn_s_barrier(); asm volatile("" ::: "memory"); } while (0)
; DI void d3_block(const Params& P, int bh, int vs, LAS unsigned char* lds, int wave, int lane, int tid) {
;     ...
;         for (int n = 0; n <= 128; ++n) {
;             if (n > 0) {
; #pragma unroll
;                 for (int j = 0; j < 4; ++j) { const f32x4 v = *(const LAS f32x4*)(ostage0 + ((n - 1) & 1) * 2304 + (row0 + 8 * j) * 36 + col4); *(f32x4*)(orow + (size_t)((n - 1) * 64 + 8 * j) * 1024) = v; } }
;             if (n < 128) D3_BAR();
;         }
.LBB0_361:
	s_add_u32 s38, s36, 0x21100000
	s_addc_u32 s39, s37, 0
	s_add_u32 s42, s36, 0x23100000
	s_addc_u32 s43, s37, 0
	global_load_dwordx4 v[216:219], v220, s[38:39]
	global_load_dwordx4 v[216:219], v220, s[38:39] offset:2048
	global_load_dwordx4 v[216:219], v220, s[42:43]
	global_load_dwordx4 v[216:219], v220, s[42:43] offset:2048
	s_add_u32 s38, s36, 0x25100000
	s_addc_u32 s39, s37, 0
	s_add_u32 s42, s36, 0x27100000
	s_addc_u32 s43, s37, 0
	global_load_dwordx4 v[216:219], v220, s[38:39]
	global_load_dwordx4 v[216:219], v220, s[38:39] offset:2048
	global_load_dwordx4 v[216:219], v220, s[42:43]
	global_load_dwordx4 v[216:219], v220, s[42:43] offset:2048
	global_load_dwordx4 v[216:219], v220, s[40:41]
	s_add_u32 s36, s36, 0x4000
	s_addc_u32 s37, s37, 0
	s_add_u32 s40, s40, 0x2000
	s_addc_u32 s41, s41, 0
	s_cmpk_eq_i32 s8, 0xffc0
	s_cselect_b64 s[0:1], -1, 0
	s_and_b64 vcc, exec, s[0:1]
	s_cbranch_vccnz .LBB0_363
	s_bitcmp1_b32 s4, 0
	s_cselect_b32 s0, 0x2400, 0
	v_add_u32_e32 v3, s0, v2
	ds_read_b128 v[4:7], v3
	s_lshl_b64 s[0:1], s[8:9], 12
	v_lshl_add_u64 v[8:9], v[0:1], 0, s[0:1]
	s_add_i32 s0, s8, 8
	s_mov_b32 s1, s9
	s_waitcnt lgkmcnt(0)
	global_store_dwordx4 v[8:9], v[4:7], off
	ds_read_b128 v[4:7], v3 offset:1152
	s_lshl_b64 s[0:1], s[0:1], 12
	v_lshl_add_u64 v[8:9], v[0:1], 0, s[0:1]
	s_add_i32 s0, s8, 16
	s_mov_b32 s1, s9
	s_waitcnt lgkmcnt(0)
	global_store_dwordx4 v[8:9], v[4:7], off
	ds_read_b128 v[4:7], v3 offset:2304
	s_lshl_b64 s[0:1], s[0:1], 12
	v_lshl_add_u64 v[8:9], v[0:1], 0, s[0:1]
	s_add_i32 s0, s8, 24
	s_mov_b32 s1, s9
	s_waitcnt lgkmcnt(0)
	global_store_dwordx4 v[8:9], v[4:7], off
	ds_read_b128 v[4:7], v3 offset:3456
	s_lshl_b64 s[0:1], s[0:1], 12
	s_cmpk_lg_i32 s8, 0x1fc0
	v_lshl_add_u64 v[8:9], v[0:1], 0, s[0:1]
	s_mov_b64 s[12:13], s[8:9]
	s_cselect_b64 s[0:1], -1, 0
	s_waitcnt lgkmcnt(0)
	global_store_dwordx4 v[8:9], v[4:7], off
	s_andn2_b64 vcc, exec, s[0:1]
	s_cbranch_vccnz .LBB0_360
	s_branch .LBB0_359
